# P9 combine: residual/gate loads overlap first expert-row fetch; tokens no expert picked are not re-read/re-written (out already x1)
# speedup vs baseline: 1.0009x; 1.0009x over previous
.LBB0_1223:
	s_or_b64 exec, exec, s[2:3]
	s_and_saveexec_b64 s[2:3], vcc
	s_cbranch_execz .LBB0_1232
	s_lshl_b32 s14, s82, 3
	v_mbcnt_lo_u32_b32 v1, -1, 0
	s_add_u32 s6, s78, 0x26400000
	v_lshlrev_b32_e32 v2, 3, v192
	v_mov_b32_e32 v33, 0
	v_lshlrev_b32_e32 v32, 5, v192
	v_mbcnt_hi_u32_b32 v1, -1, v1
	s_addc_u32 s7, s79, 0
	v_lshl_add_u64 v[34:35], s[76:77], 0, v[32:33]
	s_mov_b64 s[8:9], 0
	s_mov_b32 s15, 0xffff
	s_mov_b32 s16, 0x10000
	v_lshlrev_b32_e32 v36, 2, v2
	v_mov_b32_e32 v37, v33
	s_mov_b64 s[10:11], 0x105000
	v_and_b32_e32 v56, 64, v1
	v_lshlrev_b32_e32 v32, 1, v2
	s_waitcnt vmcnt(0)
	s_branch .LBB0_1227
.Lp9_skip:
	s_and_b64 s[2:3], exec, s[2:3]
	s_or_b64 s[8:9], s[2:3], s[8:9]
	s_waitcnt vmcnt(0)
	v_mov_b32_e32 v59, v58
	v_mov_b32_e32 v0, v57
	s_andn2_b64 exec, exec, s[8:9]
	s_cbranch_execz .LBB0_1232
	s_branch .LBB0_1227

.LBB0_1229:
	s_or_b64 exec, exec, s[12:13]
	v_cmp_lt_i32_e32 vcc, -1, v59
	s_cbranch_vccz .Lp9_skip
	v_ashrrev_i32_e32 v1, 31, v0
	v_ashrrev_i32_e32 v40, 12, v0
	v_lshlrev_b64 v[0:1], 12, v[0:1]
	v_lshl_add_u64 v[38:39], v[34:35], 0, v[0:1]
	v_mul_i32_i24_e32 v0, 0x1800, v40
	v_ashrrev_i32_e32 v1, 31, v0
	v_lshl_add_u64 v[0:1], v[0:1], 2, s[78:79]
	v_lshl_add_u64 v[0:1], v[0:1], 0, v[36:37]
	v_add_co_u32_e32 v44, vcc, 0x105000, v0
	v_lshl_add_u64 v[42:43], v[0:1], 0, s[10:11]
	global_load_dwordx4 v[16:19], v[38:39], off offset:16
	global_load_dwordx4 v[24:27], v[38:39], off
	v_addc_co_u32_e32 v45, vcc, 0, v1, vcc
	global_load_dwordx4 v[0:3], v[38:39], off offset:2064
	global_load_dwordx4 v[8:11], v[38:39], off offset:2048
	global_load_dwordx4 v[28:31], v[44:45], off
	global_load_dwordx4 v[4:7], v[42:43], off offset:2064
	global_load_dwordx4 v[20:23], v[42:43], off offset:16
	global_load_dwordx4 v[12:15], v[42:43], off offset:2048
	v_cmp_lt_i32_e32 vcc, -1, v59
	v_mov_b32_e32 v42, 0
	v_lshlrev_b32_e32 v60, 4, v40
	v_mov_b32_e32 v43, v42
	v_mov_b32_e32 v40, v42
	v_mov_b32_e32 v41, v42
	v_mov_b32_e32 v46, v42
	v_mov_b32_e32 v47, v42
	v_mov_b32_e32 v44, v42
	v_mov_b32_e32 v45, v42
	v_mov_b32_e32 v50, v42
	v_mov_b32_e32 v51, v42
	v_mov_b32_e32 v48, v42
	v_mov_b32_e32 v49, v42
	v_mov_b32_e32 v54, v42
	v_mov_b32_e32 v55, v42
	v_mov_b32_e32 v52, v42
	v_mov_b32_e32 v53, v42
